# v48: first exchange carries 1/rms (computed once per row by the summing lane, same instruction sequence) instead of the total; the eight per-row 1/sqrt sequences in every lane become moves
# speedup vs baseline: 1.0015x; 1.0015x over previous
.LBB0_639:
	s_waitcnt vmcnt(0) lgkmcnt(0)
	s_barrier
	s_and_saveexec_b64 s[22:23], s[4:5]
	s_cbranch_execz .LBB0_641
	s_mov_b64 s[10:11], 0x9000000
	v_lshl_add_u64 v[188:189], v[174:175], 0, s[10:11]
	global_load_dword v208, v[188:189], off sc1
	global_load_dword v209, v[188:189], off offset:4 sc1
	global_load_dword v214, v[188:189], off offset:8 sc1
	global_load_dword v215, v[188:189], off offset:12 sc1
	v_lshl_add_u32 v202, v226, 2, 16
	s_waitcnt vmcnt(3)
	v_add_f32_e32 v208, 0, v208
	s_waitcnt vmcnt(2)
	v_add_f32_e32 v208, v208, v209
	s_waitcnt vmcnt(1)
	v_add_f32_e32 v208, v208, v214
	s_waitcnt vmcnt(0)
	v_add_f32_e32 v208, v208, v215
	v_fmamk_f32 v208, v208, 0x3a800000, v222
	v_mul_f32_e32 v209, 0x4f800000, v208
	v_cmp_gt_f32_e32 vcc, s73, v208
	s_nop 1
	v_cndmask_b32_e32 v208, v208, v209, vcc
	v_sqrt_f32_e32 v209, v208
	s_nop 0
	v_add_u32_e32 v214, -1, v209
	v_fma_f32 v188, -v214, v209, v208
	v_add_u32_e32 v215, 1, v209
	v_cmp_ge_f32_e64 s[10:11], 0, v188
	s_nop 1
	v_cndmask_b32_e64 v214, v209, v214, s[10:11]
	v_fma_f32 v209, -v215, v209, v208
	v_cmp_lt_f32_e64 s[10:11], 0, v209
	s_nop 1
	v_cndmask_b32_e64 v209, v214, v215, s[10:11]
	v_mul_f32_e32 v214, 0x37800000, v209
	v_cndmask_b32_e32 v209, v209, v214, vcc
	v_cmp_class_f32_e32 vcc, v208, v247
	s_nop 1
	v_cndmask_b32_e32 v208, v209, v208, vcc
	v_div_scale_f32 v209, s[2:3], v208, v208, 1.0
	v_rcp_f32_e32 v214, v209
	s_nop 0
	v_fma_f32 v215, -v209, v214, 1.0
	v_fmac_f32_e32 v214, v215, v214
	v_div_scale_f32 v215, vcc, 1.0, v208, 1.0
	v_mul_f32_e32 v188, v215, v214
	v_fma_f32 v189, -v209, v188, v215
	v_fmac_f32_e32 v188, v189, v214
	v_fma_f32 v209, -v209, v188, v215
	v_div_fmas_f32 v209, v209, v214, v188
	v_div_fixup_f32 v208, v209, v208, 1.0
	ds_write_b32 v202, v208 offset:4096
.LBB0_641:
	s_or_b64 exec, exec, s[22:23]
	s_waitcnt vmcnt(0) lgkmcnt(0)
	s_barrier
	ds_read2_b32 v[188:189], v228 offset1:16
	ds_read2_b32 v[214:215], v228 offset0:32 offset1:48
	ds_read2_b32 v[208:209], v228 offset0:128 offset1:144
	ds_read2_b32 v[202:203], v228 offset0:160 offset1:176
	s_waitcnt lgkmcnt(0)
	s_barrier
	s_waitcnt lgkmcnt(0)
	s_cmp_eq_u64 s[20:21], 0
	s_cselect_b64 s[22:23], -1, 0
	s_cmp_lg_u64 s[20:21], 0
	s_cselect_b64 s[12:13], -1, 0
	s_mov_b64 s[10:11], -1
	v_pk_mul_f32 v[128:129], v[128:129], v[188:189] op_sel_hi:[1,0]
	v_pk_mul_f32 v[130:131], v[130:131], v[188:189] op_sel_hi:[1,0]
	v_lshlrev_b64 v[200:201], 10, v[168:169]
	v_pk_mul_f32 v[124:125], v[124:125], v[188:189] op_sel_hi:[1,0]
	v_pk_mul_f32 v[126:127], v[126:127], v[188:189] op_sel_hi:[1,0]
	s_and_b64 vcc, exec, s[22:23]
	s_waitcnt vmcnt(0)
	v_lshlrev_b32_e32 v198, 16, v216
	v_and_b32_e32 v199, 0xffff0000, v216
	v_lshlrev_b32_e32 v216, 16, v217
	v_and_b32_e32 v217, 0xffff0000, v217
	v_pk_fma_f32 v[130:131], v[130:131], v[138:139], v[216:217]
	v_pk_fma_f32 v[128:129], v[128:129], v[136:137], v[198:199]
	v_lshlrev_b32_e32 v198, 16, v218
	v_and_b32_e32 v199, 0xffff0000, v218
	v_lshlrev_b32_e32 v216, 16, v219
	v_and_b32_e32 v217, 0xffff0000, v219
	v_pk_fma_f32 v[126:127], v[126:127], v[134:135], v[216:217]
	v_pk_fma_f32 v[124:125], v[124:125], v[132:133], v[198:199]
	v_lshl_add_u64 v[198:199], v[200:201], 2, s[20:21]
	s_cbranch_vccnz .LBB0_643
	v_lshl_add_u64 v[216:217], v[176:177], 2, v[198:199]
	s_mov_b64 s[10:11], 0
	global_store_dwordx4 v[216:217], v[128:131], off
	global_store_dwordx4 v[216:217], v[124:127], off offset:16

.LBB0_645:
	v_mov_b32_e32 v124, v189
	v_lshlrev_b32_e32 v130, 16, v165
	v_and_b32_e32 v131, 0xffff0000, v165
	s_mov_b64 s[26:27], -1
	v_lshlrev_b32_e32 v126, 16, v164
	v_and_b32_e32 v127, 0xffff0000, v164
	v_pk_mul_f32 v[120:121], v[120:121], v[124:125] op_sel_hi:[1,0]
	v_pk_mul_f32 v[122:123], v[122:123], v[124:125] op_sel_hi:[1,0]
	v_lshlrev_b64 v[128:129], 10, v[172:173]
	v_pk_fma_f32 v[122:123], v[122:123], v[138:139], v[130:131]
	v_pk_fma_f32 v[120:121], v[120:121], v[136:137], v[126:127]
	v_lshlrev_b32_e32 v126, 16, v166
	v_and_b32_e32 v127, 0xffff0000, v166
	v_lshlrev_b32_e32 v130, 16, v167
	v_and_b32_e32 v131, 0xffff0000, v167
	v_pk_mul_f32 v[116:117], v[116:117], v[124:125] op_sel_hi:[1,0]
	v_pk_mul_f32 v[118:119], v[118:119], v[124:125] op_sel_hi:[1,0]
	v_cndmask_b32_e64 v125, 0, 1, s[12:13]
	v_pk_fma_f32 v[118:119], v[118:119], v[134:135], v[130:131]
	v_pk_fma_f32 v[116:117], v[116:117], v[132:133], v[126:127]
	v_cmp_ne_u32_e64 s[10:11], 1, v125
	s_andn2_b64 vcc, exec, s[12:13]
	v_lshl_add_u64 v[126:127], v[128:129], 2, s[20:21]
	s_cbranch_vccnz .LBB0_647
	v_lshl_add_u64 v[130:131], v[176:177], 2, v[126:127]
	s_mov_b64 s[26:27], 0
	global_store_dwordx4 v[130:131], v[120:123], off
	global_store_dwordx4 v[130:131], v[116:119], off offset:16

.LBB0_649:
	v_mov_b32_e32 v116, v214
	v_lshlrev_b32_e32 v122, 16, v161
	v_and_b32_e32 v123, 0xffff0000, v161
	s_mov_b64 s[12:13], -1
	v_lshlrev_b32_e32 v118, 16, v160
	v_and_b32_e32 v119, 0xffff0000, v160
	v_pk_mul_f32 v[112:113], v[112:113], v[116:117] op_sel_hi:[1,0]
	v_pk_mul_f32 v[114:115], v[114:115], v[116:117] op_sel_hi:[1,0]
	v_lshlrev_b64 v[120:121], 10, v[170:171]
	v_pk_fma_f32 v[114:115], v[114:115], v[138:139], v[122:123]
	v_pk_fma_f32 v[112:113], v[112:113], v[136:137], v[118:119]
	v_lshlrev_b32_e32 v118, 16, v162
	v_and_b32_e32 v119, 0xffff0000, v162
	v_lshlrev_b32_e32 v122, 16, v163
	v_and_b32_e32 v123, 0xffff0000, v163
	v_pk_mul_f32 v[108:109], v[108:109], v[116:117] op_sel_hi:[1,0]
	v_pk_mul_f32 v[110:111], v[110:111], v[116:117] op_sel_hi:[1,0]
	v_pk_fma_f32 v[108:109], v[108:109], v[132:133], v[118:119]
	v_pk_fma_f32 v[110:111], v[110:111], v[134:135], v[122:123]
	s_and_b64 vcc, exec, s[10:11]
	v_lshl_add_u64 v[118:119], v[120:121], 2, s[20:21]
	s_cbranch_vccnz .LBB0_651
	v_lshl_add_u64 v[122:123], v[176:177], 2, v[118:119]
	s_mov_b64 s[12:13], 0
	global_store_dwordx4 v[122:123], v[112:115], off
	global_store_dwordx4 v[122:123], v[108:111], off offset:16

.LBB0_653:
	v_mov_b32_e32 v108, v215
	v_lshlrev_b32_e32 v114, 16, v157
	v_and_b32_e32 v115, 0xffff0000, v157
	s_mov_b64 s[12:13], -1
	v_lshlrev_b32_e32 v110, 16, v156
	v_and_b32_e32 v111, 0xffff0000, v156
	v_pk_mul_f32 v[104:105], v[104:105], v[108:109] op_sel_hi:[1,0]
	v_pk_mul_f32 v[106:107], v[106:107], v[108:109] op_sel_hi:[1,0]
	v_lshlrev_b64 v[112:113], 10, v[0:1]
	v_pk_fma_f32 v[106:107], v[106:107], v[138:139], v[114:115]
	v_pk_fma_f32 v[104:105], v[104:105], v[136:137], v[110:111]
	v_lshlrev_b32_e32 v110, 16, v158
	v_and_b32_e32 v111, 0xffff0000, v158
	v_lshlrev_b32_e32 v114, 16, v159
	v_and_b32_e32 v115, 0xffff0000, v159
	v_pk_mul_f32 v[100:101], v[100:101], v[108:109] op_sel_hi:[1,0]
	v_pk_mul_f32 v[102:103], v[102:103], v[108:109] op_sel_hi:[1,0]
	v_pk_fma_f32 v[100:101], v[100:101], v[132:133], v[110:111]
	v_pk_fma_f32 v[102:103], v[102:103], v[134:135], v[114:115]
	s_and_b64 vcc, exec, s[10:11]
	v_lshl_add_u64 v[110:111], v[112:113], 2, s[20:21]
	s_cbranch_vccnz .LBB0_655
	v_lshl_add_u64 v[114:115], v[176:177], 2, v[110:111]
	s_mov_b64 s[12:13], 0
	global_store_dwordx4 v[114:115], v[104:107], off
	global_store_dwordx4 v[114:115], v[100:103], off offset:16

.LBB0_657:
	v_mov_b32_e32 v104, v208
	v_lshlrev_b32_e32 v106, 16, v153
	v_and_b32_e32 v107, 0xffff0000, v153
	s_mov_b64 s[12:13], -1
	v_lshlrev_b32_e32 v102, 16, v152
	v_and_b32_e32 v103, 0xffff0000, v152
	v_pk_mul_f32 v[96:97], v[96:97], v[104:105] op_sel_hi:[1,0]
	v_pk_mul_f32 v[98:99], v[98:99], v[104:105] op_sel_hi:[1,0]
	v_lshlrev_b64 v[100:101], 10, v[212:213]
	v_pk_fma_f32 v[98:99], v[138:139], v[98:99], v[106:107]
	v_pk_fma_f32 v[96:97], v[136:137], v[96:97], v[102:103]
	v_lshlrev_b32_e32 v102, 16, v154
	v_and_b32_e32 v103, 0xffff0000, v154
	v_lshlrev_b32_e32 v106, 16, v155
	v_and_b32_e32 v107, 0xffff0000, v155
	v_pk_mul_f32 v[92:93], v[92:93], v[104:105] op_sel_hi:[1,0]
	v_pk_mul_f32 v[94:95], v[94:95], v[104:105] op_sel_hi:[1,0]
	v_pk_fma_f32 v[92:93], v[92:93], v[132:133], v[102:103]
	v_pk_fma_f32 v[94:95], v[94:95], v[134:135], v[106:107]
	s_and_b64 vcc, exec, s[10:11]
	v_lshl_add_u64 v[106:107], v[100:101], 2, s[20:21]
	s_cbranch_vccnz .LBB0_659
	v_lshl_add_u64 v[102:103], v[176:177], 2, v[106:107]
	s_mov_b64 s[12:13], 0
	global_store_dwordx4 v[102:103], v[96:99], off
	global_store_dwordx4 v[102:103], v[92:95], off offset:16

.LBB0_661:
	v_mov_b32_e32 v122, v209
	s_mov_b64 s[12:13], -1
	v_lshlrev_b32_e32 v94, 16, v148
	v_and_b32_e32 v95, 0xffff0000, v148
	v_lshlrev_b32_e32 v96, 16, v149
	v_and_b32_e32 v97, 0xffff0000, v149
	v_pk_mul_f32 v[88:89], v[88:89], v[122:123] op_sel_hi:[1,0]
	v_pk_mul_f32 v[90:91], v[90:91], v[122:123] op_sel_hi:[1,0]
	v_lshlrev_b64 v[92:93], 10, v[210:211]
	v_pk_fma_f32 v[90:91], v[138:139], v[90:91], v[96:97]
	v_pk_fma_f32 v[88:89], v[136:137], v[88:89], v[94:95]
	v_lshlrev_b32_e32 v94, 16, v150
	v_and_b32_e32 v95, 0xffff0000, v150
	v_lshlrev_b32_e32 v96, 16, v151
	v_and_b32_e32 v97, 0xffff0000, v151
	v_pk_mul_f32 v[84:85], v[84:85], v[122:123] op_sel_hi:[1,0]
	v_pk_mul_f32 v[86:87], v[86:87], v[122:123] op_sel_hi:[1,0]
	v_pk_fma_f32 v[84:85], v[132:133], v[84:85], v[94:95]
	v_pk_fma_f32 v[86:87], v[134:135], v[86:87], v[96:97]
	s_and_b64 vcc, exec, s[10:11]
	v_lshl_add_u64 v[130:131], v[92:93], 2, s[20:21]
	s_cbranch_vccnz .LBB0_663
	v_lshl_add_u64 v[94:95], v[176:177], 2, v[130:131]
	s_mov_b64 s[12:13], 0
	global_store_dwordx4 v[94:95], v[88:91], off
	global_store_dwordx4 v[94:95], v[84:87], off offset:16

.LBB0_665:
	v_mov_b32_e32 v150, v202
	s_mov_b64 s[12:13], -1
	v_lshlrev_b32_e32 v86, 16, v144
	v_and_b32_e32 v87, 0xffff0000, v144
	v_lshlrev_b32_e32 v88, 16, v145
	v_and_b32_e32 v89, 0xffff0000, v145
	v_pk_mul_f32 v[80:81], v[80:81], v[150:151] op_sel_hi:[1,0]
	v_pk_mul_f32 v[82:83], v[82:83], v[150:151] op_sel_hi:[1,0]
	v_lshlrev_b64 v[84:85], 10, v[206:207]
	v_pk_fma_f32 v[82:83], v[138:139], v[82:83], v[88:89]
	v_pk_fma_f32 v[80:81], v[136:137], v[80:81], v[86:87]
	v_lshlrev_b32_e32 v86, 16, v146
	v_and_b32_e32 v87, 0xffff0000, v146
	v_lshlrev_b32_e32 v88, 16, v147
	v_and_b32_e32 v89, 0xffff0000, v147
	v_pk_mul_f32 v[76:77], v[76:77], v[150:151] op_sel_hi:[1,0]
	v_pk_mul_f32 v[78:79], v[78:79], v[150:151] op_sel_hi:[1,0]
	v_pk_fma_f32 v[76:77], v[132:133], v[76:77], v[86:87]
	v_pk_fma_f32 v[78:79], v[134:135], v[78:79], v[88:89]
	s_and_b64 vcc, exec, s[10:11]
	v_lshl_add_u64 v[144:145], v[84:85], 2, s[20:21]
	s_cbranch_vccnz .LBB0_667
	v_lshl_add_u64 v[86:87], v[176:177], 2, v[144:145]
	s_mov_b64 s[12:13], 0
	global_store_dwordx4 v[86:87], v[80:83], off
	global_store_dwordx4 v[86:87], v[76:79], off offset:16

.LBB0_669:
	v_mov_b32_e32 v152, v203
	s_mov_b64 s[12:13], -1
	v_lshlrev_b32_e32 v78, 16, v140
	v_and_b32_e32 v79, 0xffff0000, v140
	v_lshlrev_b32_e32 v80, 16, v141
	v_and_b32_e32 v81, 0xffff0000, v141
	v_pk_mul_f32 v[72:73], v[72:73], v[152:153] op_sel_hi:[1,0]
	v_pk_mul_f32 v[74:75], v[74:75], v[152:153] op_sel_hi:[1,0]
	v_lshlrev_b64 v[76:77], 10, v[204:205]
	v_pk_fma_f32 v[74:75], v[138:139], v[74:75], v[80:81]
	v_pk_fma_f32 v[72:73], v[136:137], v[72:73], v[78:79]
	v_lshlrev_b32_e32 v78, 16, v142
	v_and_b32_e32 v79, 0xffff0000, v142
	v_lshlrev_b32_e32 v80, 16, v143
	v_and_b32_e32 v81, 0xffff0000, v143
	v_pk_mul_f32 v[68:69], v[68:69], v[152:153] op_sel_hi:[1,0]
	v_pk_mul_f32 v[70:71], v[70:71], v[152:153] op_sel_hi:[1,0]
	v_pk_fma_f32 v[68:69], v[132:133], v[68:69], v[78:79]
	v_pk_fma_f32 v[70:71], v[134:135], v[70:71], v[80:81]
	s_and_b64 vcc, exec, s[10:11]
	v_lshl_add_u64 v[132:133], v[76:77], 2, s[20:21]
	s_cbranch_vccnz .LBB0_671
	v_lshl_add_u64 v[78:79], v[176:177], 2, v[132:133]
	s_mov_b64 s[12:13], 0
	global_store_dwordx4 v[78:79], v[72:75], off
	global_store_dwordx4 v[78:79], v[68:71], off offset:16
